# blocked ACT layout (16x32 blocks, contiguous 1KB stores) for layer-0 SwiGLU output; down GEMM gathers blocks
# speedup vs baseline: 1.0076x; 1.0076x over previous
; #define PG8_STAGE(bufoff, gbase, voff) do { _Pragma("unroll") for (int _i = 0; _i < 2; ++_i) \
;         __builtin_amdgcn_global_load_lds((const unsigned*)((const char*)(gbase) + (voff)[_i]), (PG8_LAS unsigned*)(lds + (bufoff) + ldsw + _i * 8192), 16, 0, 0); } while (0)
; #define PG8_WAIT_V(n) asm volatile("s_waitcnt vmcnt(" #n ")" ::: "memory")
; #define PG8_BAR __builtin_amdgcn_s_barrier()
; template <class Epi, class Sched, bool ALIGN_EPI = false, bool SP2 = false>
; __device__ __forceinline__ void gemm_phase(PG8_LAS unsigned char* lds, const Gemm g, const Sched& S, const Epi& E) {
;     ...
;         PG8_STAGE(PG8_SB(0, 0), cB, voffB); PG8_STAGE(PG8_SB(0, 1), cB + hstepB, voffB); PG8_STAGE(PG8_SA(0, 0), cA, voffA); PG8_STAGE(PG8_SA(0, 1), cA + hstepA, voffA);
;         if (wr == 1) PG8_BAR;
;         PG8_WAIT_V(2); PG8_BAR;
;         PG8_STAGE(PG8_SB(1, 0), cB + kstep, voffB); PG8_STAGE(PG8_SA(1, 0), cA + kstep, voffA); PG8_STAGE(PG8_SB(1, 1), cB + hstepB + kstep, voffB);
;         PG8_WAIT_V(6); PG8_BAR;
;     __device__ __forceinline__ void operator()(const pg8::f32x4 (&acc)[2][2][4][2], const Unit& u, int wr, int wc, int fr, int fq) const {
;         const int row0 = u.pm * BM + wr * 64 + fr, col0 = u.pn * HALF + wc * 32 + 8 * fq;
;         float rsv[8]; rstd8(ss, row0, fq, rsv);
.LBB0_685:
	s_add_u32 s8, s78, 0x13c00000
	s_addc_u32 s9, s79, 0
	s_lshl_b32 s10, s10, 5
	s_and_b32 s16, s10, 0x60
	s_mov_b64 s[10:11], 0x80
	s_add_i32 m0, s23, 0x18000
	v_lshl_add_u64 v[8:9], v[8:9], 0, s[10:11]
	s_lshl_b32 s13, s12, 13
	s_lshl_b32 s17, s16, 7
	s_waitcnt vmcnt(2)
	s_barrier
	global_load_lds_dwordx4 v[8:9], off
	v_lshl_add_u64 v[6:7], v[6:7], 0, s[10:11]
	s_add_i32 m0, s23, 0x1a000
	s_add_i32 s38, s23, 0x8000
	s_add_i32 s39, s23, 0xa000
	global_load_lds_dwordx4 v[6:7], off
	v_lshl_add_u64 v[2:3], v[2:3], 0, s[10:11]
	s_mov_b32 m0, s38
	s_add_u32 s14, s26, 0x40080
	global_load_lds_dwordx4 v[2:3], off
	v_lshl_add_u64 v[2:3], v[4:5], 0, s[10:11]
	s_mov_b32 m0, s39
	s_addc_u32 s15, s27, 0
	global_load_lds_dwordx4 v[2:3], off
	s_add_i32 m0, s23, 0x1c000
	v_lshl_add_u64 v[2:3], s[14:15], 0, v[134:135]
	global_load_lds_dwordx4 v[2:3], off
	v_lshl_add_u64 v[2:3], s[14:15], 0, v[130:131]
	s_add_i32 m0, s23, 0x1e000
	v_bfe_u32 v4, v12, 4, 2
	global_load_lds_dwordx4 v[2:3], off
	v_and_b32_e32 v3, 15, v12
	v_lshlrev_b32_e32 v2, 4, v4
	v_lshlrev_b32_e32 v5, 2, v12
	v_lshl_or_b32 v1, s12, 6, v3
	v_lshl_or_b32 v3, v3, 6, v2
	v_and_b32_e32 v5, 32, v5
	v_bitop3_b32 v6, v3, s13, v5 bitop3:0xde
	v_bitop3_b32 v166, v3, s17, v5 bitop3:0xde
	v_mov_b32_e32 v3, v135
	s_sext_i32_i8 s45, s6
	s_cmpk_lt_u32 s7, 0x100
	v_lshl_add_u64 v[2:3], s[78:79], 0, v[2:3]
	s_mov_b64 s[6:7], 0x5a00000
	v_lshl_add_u64 v[138:139], v[2:3], 0, s[6:7]
	v_lshlrev_b32_e32 v2, 14, v15
	v_and_b32_e32 v2, 0xffff8000, v2
	v_lshl_add_u32 v2, v14, 11, v2
	v_and_b32_e32 v3, 1, v15
	v_lshl_or_b32 v2, v3, 6, v2
	v_lshl_add_u32 v140, v16, 1, v2
	v_lshlrev_b32_e32 v2, 14, v10
	v_and_b32_e32 v2, 0xffff8000, v2
	v_lshl_add_u32 v2, v11, 11, v2
	v_and_b32_e32 v3, 1, v10
	s_waitcnt vmcnt(6)
	v_lshl_or_b32 v2, v3, 6, v2
	s_cselect_b64 s[12:13], -1, 0
	v_lshl_add_u32 v142, v13, 1, v2
	s_add_i32 s42, 0, 0x10000
	s_add_i32 s43, 0, 0x14000
	v_mbcnt_lo_u32_b32 v2, -1, 0
	s_ashr_i32 s40, s82, 31
	s_mov_b32 s41, s82
	v_and_b32_e32 v167, 15, v12
	v_mul_i32_i24_e32 v167, 0xfffff508, v167
	v_lshl_add_u32 v167, v4, 7, v167
	s_lshl_b32 s99, s16, 4
	v_add_u32_e32 v167, s99, v167
	v_mov_b32_e32 v141, v135
	v_mov_b32_e32 v143, v135
	v_mov_b64_e32 v[144:145], 0xb00
	v_mov_b64_e32 v[146:147], 0xaff
	v_add_u32_e32 v168, s42, v166
	v_add_u32_e32 v169, s43, v166
	v_add_u32_e32 v170, 0, v6
	v_mbcnt_hi_u32_b32 v171, -1, v2
	v_mov_b32_e32 v172, 0x358637bd
	s_movk_i32 s44, 0x1600
	s_barrier
	s_branch .LBB0_688

; __device__ __forceinline__ unsigned cvt_pk_bf16(float lo, float hi) { unsigned r; asm volatile("v_cvt_pk_bf16_f32 %0, %1, %2" : "=v"(r) : "v"(lo), "v"(hi)); return r; }
; __device__ __forceinline__ void rstd8(const float* ss, int row0, int fq, float (&rs)[8]) {
;     f32x4 a[8];
; #pragma unroll
;     for (int k = 0; k < 8; ++k) a[k] = *(const f32x4*)(ss + (size_t)(row0 + (k >> 2) * 128 + (k & 3) * 16) * 16 + 4 * fq);
; #pragma unroll
;     for (int k = 0; k < 8; ++k) { float s = (a[k][0] + a[k][1]) + (a[k][2] + a[k][3]); s += __shfl_xor(s, 16); s += __shfl_xor(s, 32); rs[k] = __builtin_amdgcn_rsqf(s * (1.f / 1024.f) + EPS); }
; }
;     __device__ __forceinline__ void operator()(const pg8::f32x4 (&acc)[2][2][4][2], const Unit& u, int wr, int wc, int fr, int fq) const {
;         const int row0 = u.pm * BM + wr * 64 + fr, col0 = u.pn * HALF + wc * 32 + 8 * fq;
;         float rsv[8]; rstd8(ss, row0, fq, rsv);
; #pragma unroll
;         for (int ai = 0; ai < 2; ++ai)
; #pragma unroll
;             for (int m = 0; m < 4; ++m) { float r[8]; const float rs = rsv[ai * 4 + m]; const float c1 = -1.4426950408889634f * rs, rs2 = rs * rs;
; #pragma unroll
;                 for (int n = 0; n < 2; ++n)
; #pragma unroll
;                     for (int e = 0; e < 4; e += 2) { const f32x2 ag = {acc[ai][0][m][n][e], acc[ai][0][m][n][e + 1]}, au = {acc[ai][1][m][n][e], acc[ai][1][m][n][e + 1]};
;                         const f32x2 t = ag * c1; f32x2 d; d.x = __builtin_amdgcn_exp2f(t.x); d.y = __builtin_amdgcn_exp2f(t.y); d = d + 1.0f;
;                         f32x2 q; q.x = __builtin_amdgcn_rcpf(d.x); q.y = __builtin_amdgcn_rcpf(d.y); const f32x2 o = (ag * au) * rs2 * q; r[4 * n + e] = o.x; r[4 * n + e + 1] = o.y; }
;                 v4u w; w.x = cvt_pk_bf16(r[0], r[1]); w.y = cvt_pk_bf16(r[2], r[3]); w.z = cvt_pk_bf16(r[4], r[5]); w.w = cvt_pk_bf16(r[6], r[7]);
;                 __builtin_nontemporal_store(w, (v4u*)(O + (size_t)(row0 + ai * HALF + m * 16) * FF + col0)); }
.LBB0_694:
	v_lshl_add_u32 v162, s22, 8, v1
	v_ashrrev_i32_e32 v163, 31, v162
	v_or_b32_e32 v160, 16, v162
	v_lshlrev_b64 v[148:149], 6, v[162:163]
	v_ashrrev_i32_e32 v161, 31, v160
	v_or_b32_e32 v158, 32, v162
	v_lshl_add_u64 v[148:149], v[138:139], 0, v[148:149]
	v_lshlrev_b64 v[150:151], 6, v[160:161]
	v_ashrrev_i32_e32 v159, 31, v158
	v_or_b32_e32 v156, 48, v162
	v_lshl_add_u64 v[150:151], v[138:139], 0, v[150:151]
	global_load_dwordx4 v[174:177], v[148:149], off
	global_load_dwordx4 v[178:181], v[150:151], off
	v_lshlrev_b64 v[148:149], 6, v[158:159]
	v_ashrrev_i32_e32 v157, 31, v156
	v_lshl_add_u64 v[148:149], v[138:139], 0, v[148:149]
	v_lshlrev_b64 v[150:151], 6, v[156:157]
	v_lshl_add_u64 v[150:151], v[138:139], 0, v[150:151]
	global_load_dwordx4 v[182:185], v[148:149], off
	global_load_dwordx4 v[186:189], v[150:151], off
	v_add_u32_e32 v154, 0x80, v162
	v_ashrrev_i32_e32 v155, 31, v154
	v_lshlrev_b64 v[148:149], 6, v[154:155]
	v_lshl_add_u64 v[148:149], v[138:139], 0, v[148:149]
	global_load_dwordx4 v[190:193], v[148:149], off
	v_add_u32_e32 v152, 0x90, v162
	v_ashrrev_i32_e32 v153, 31, v152
	v_lshlrev_b64 v[148:149], 6, v[152:153]
	v_add_u32_e32 v150, 0xa0, v162
	v_lshl_add_u64 v[148:149], v[138:139], 0, v[148:149]
	v_ashrrev_i32_e32 v151, 31, v150
	global_load_dwordx4 v[194:197], v[148:149], off
	v_lshlrev_b64 v[148:149], 6, v[150:151]
	v_lshl_add_u64 v[148:149], v[138:139], 0, v[148:149]
	global_load_dwordx4 v[198:201], v[148:149], off
	v_add_u32_e32 v148, 0xb0, v162
	v_ashrrev_i32_e32 v149, 31, v148
	v_lshlrev_b64 v[202:203], 6, v[148:149]
	v_lshl_add_u64 v[202:203], v[138:139], 0, v[202:203]
	global_load_dwordx4 v[202:205], v[202:203], off
	v_and_b32_e32 v151, 64, v171
	v_xor_b32_e32 v149, 16, v171
	v_add_u32_e32 v151, 64, v151
	v_xor_b32_e32 v153, 32, v171
	v_cmp_lt_i32_e32 vcc, v149, v151
	v_pk_mul_f32 v[124:125], v[128:129], v[124:125]
	v_pk_mul_f32 v[122:123], v[126:127], v[122:123]
	v_cndmask_b32_e32 v149, v171, v149, vcc
	v_cmp_lt_i32_e32 vcc, v153, v151
	v_lshlrev_b32_e32 v149, 2, v149
	v_pk_mul_f32 v[114:115], v[118:119], v[114:115]
	v_cndmask_b32_e32 v151, v171, v153, vcc
	v_lshlrev_b32_e32 v151, 2, v151
	v_pk_mul_f32 v[116:117], v[120:121], v[116:117]
	v_lshl_add_u32 v164, s45, 11, v167
	v_pk_mul_f32 v[108:109], v[112:113], v[108:109]
	v_pk_mul_f32 v[106:107], v[110:111], v[106:107]
	v_pk_mul_f32 v[98:99], v[102:103], v[98:99]
	v_pk_mul_f32 v[100:101], v[104:105], v[100:101]
	v_pk_mul_f32 v[92:93], v[96:97], v[92:93]
	v_pk_mul_f32 v[90:91], v[94:95], v[90:91]
	v_pk_mul_f32 v[82:83], v[86:87], v[82:83]
	v_pk_mul_f32 v[84:85], v[88:89], v[84:85]
	v_pk_mul_f32 v[76:77], v[80:81], v[76:77]
	v_pk_mul_f32 v[74:75], v[78:79], v[74:75]
	v_pk_mul_f32 v[66:67], v[70:71], v[66:67]
	v_pk_mul_f32 v[68:69], v[72:73], v[68:69]
	v_pk_mul_f32 v[60:61], v[64:65], v[60:61]
	v_pk_mul_f32 v[58:59], v[62:63], v[58:59]
	v_pk_mul_f32 v[50:51], v[54:55], v[50:51]
	v_pk_mul_f32 v[52:53], v[56:57], v[52:53]
	v_pk_mul_f32 v[44:45], v[48:49], v[44:45]
	v_pk_mul_f32 v[42:43], v[46:47], v[42:43]
	v_pk_mul_f32 v[34:35], v[38:39], v[34:35]
	v_pk_mul_f32 v[36:37], v[40:41], v[36:37]
	v_pk_mul_f32 v[28:29], v[32:33], v[28:29]
	v_pk_mul_f32 v[26:27], v[30:31], v[26:27]
	v_pk_mul_f32 v[18:19], v[22:23], v[18:19]
	v_pk_mul_f32 v[20:21], v[24:25], v[20:21]
	v_pk_mul_f32 v[12:13], v[16:17], v[12:13]
	v_pk_mul_f32 v[10:11], v[14:15], v[10:11]
	v_pk_mul_f32 v[2:3], v[6:7], v[2:3]
	v_pk_mul_f32 v[4:5], v[8:9], v[4:5]
	s_andn2_b64 vcc, exec, s[6:7]
	s_mov_b64 s[6:7], -1
	s_waitcnt vmcnt(0)
	v_mov_b32_e32 v206, v175
	v_mov_b32_e32 v207, v176
	v_mov_b32_e32 v175, v177
	v_pk_add_f32 v[174:175], v[206:207], v[174:175]
	v_mov_b32_e32 v176, v179
	v_mov_b32_e32 v177, v180
	v_mov_b32_e32 v179, v181
	v_mov_b32_e32 v180, v183
	v_mov_b32_e32 v181, v184
	v_mov_b32_e32 v183, v185
	v_mov_b32_e32 v184, v187
	v_mov_b32_e32 v185, v188
	v_mov_b32_e32 v187, v189
	v_add_f32_e32 v153, v174, v175
	v_pk_add_f32 v[174:175], v[176:177], v[178:179]
	v_pk_add_f32 v[176:177], v[180:181], v[182:183]
	v_pk_add_f32 v[178:179], v[184:185], v[186:187]
	v_add_f32_e32 v157, v174, v175
	v_add_f32_e32 v159, v176, v177
	v_add_f32_e32 v161, v178, v179
	ds_bpermute_b32 v155, v149, v153
	ds_bpermute_b32 v165, v149, v157
	ds_bpermute_b32 v173, v149, v159
	ds_bpermute_b32 v174, v149, v161
	v_mov_b32_e32 v188, v191
	v_mov_b32_e32 v189, v192
	v_mov_b32_e32 v191, v193
	v_pk_add_f32 v[180:181], v[188:189], v[190:191]
	s_waitcnt lgkmcnt(3)
	v_add_f32_e32 v153, v153, v155
	v_add_f32_e32 v163, v180, v181
	s_waitcnt lgkmcnt(2)
	v_add_f32_e32 v157, v157, v165
	s_waitcnt lgkmcnt(1)
	v_add_f32_e32 v159, v159, v173
	s_waitcnt lgkmcnt(0)
	v_add_f32_e32 v161, v161, v174
	ds_bpermute_b32 v175, v149, v163
	ds_bpermute_b32 v155, v151, v153
	ds_bpermute_b32 v165, v151, v157
	ds_bpermute_b32 v173, v151, v159
	ds_bpermute_b32 v174, v151, v161
	s_waitcnt lgkmcnt(4)
	v_add_f32_e32 v163, v163, v175
	s_waitcnt lgkmcnt(3)
	v_add_f32_e32 v153, v153, v155
	s_waitcnt lgkmcnt(2)
	v_add_f32_e32 v155, v157, v165
	s_waitcnt lgkmcnt(1)
	v_add_f32_e32 v157, v159, v173
	s_waitcnt lgkmcnt(0)
	v_add_f32_e32 v159, v161, v174
	v_mov_b32_e32 v174, v195
	v_mov_b32_e32 v175, v196
	v_mov_b32_e32 v195, v197
	v_pk_add_f32 v[174:175], v[174:175], v[194:195]
	ds_bpermute_b32 v176, v151, v163
	v_add_f32_e32 v161, v174, v175
	v_mov_b32_e32 v174, v199
	v_mov_b32_e32 v175, v200
	v_mov_b32_e32 v199, v201
	v_pk_add_f32 v[174:175], v[174:175], v[198:199]
	ds_bpermute_b32 v165, v149, v161
	v_add_f32_e32 v173, v174, v175
	v_mov_b32_e32 v174, v203
	v_mov_b32_e32 v175, v204
	v_mov_b32_e32 v203, v205
	v_pk_add_f32 v[174:175], v[174:175], v[202:203]
	s_waitcnt lgkmcnt(1)
; __device__ __forceinline__ unsigned cvt_pk_bf16(float lo, float hi) { unsigned r; asm volatile("v_cvt_pk_bf16_f32 %0, %1, %2" : "=v"(r) : "v"(lo), "v"(hi)); return r; }
; __device__ __forceinline__ void rstd8(const float* ss, int row0, int fq, float (&rs)[8]) {
;     ...
;     for (int k = 0; k < 8; ++k) { float s = (a[k][0] + a[k][1]) + (a[k][2] + a[k][3]); s += __shfl_xor(s, 16); s += __shfl_xor(s, 32); rs[k] = __builtin_amdgcn_rsqf(s * (1.f / 1024.f) + EPS); }
;     __device__ __forceinline__ void operator()(const pg8::f32x4 (&acc)[2][2][4][2], const Unit& u, int wr, int wc, int fr, int fq) const {
;     ...
;             for (int m = 0; m < 4; ++m) { float r[8]; const float rs = rsv[ai * 4 + m]; const float c1 = -1.4426950408889634f * rs, rs2 = rs * rs;
; #pragma unroll
;                 for (int n = 0; n < 2; ++n)
; #pragma unroll
;                     for (int e = 0; e < 4; e += 2) { const f32x2 ag = {acc[ai][0][m][n][e], acc[ai][0][m][n][e + 1]}, au = {acc[ai][1][m][n][e], acc[ai][1][m][n][e + 1]};
;                         const f32x2 t = ag * c1; f32x2 d; d.x = __builtin_amdgcn_exp2f(t.x); d.y = __builtin_amdgcn_exp2f(t.y); d = d + 1.0f;
;                         f32x2 q; q.x = __builtin_amdgcn_rcpf(d.x); q.y = __builtin_amdgcn_rcpf(d.y); const f32x2 o = (ag * au) * rs2 * q; r[4 * n + e] = o.x; r[4 * n + e + 1] = o.y; }
;                 v4u w; w.x = cvt_pk_bf16(r[0], r[1]); w.y = cvt_pk_bf16(r[2], r[3]); w.z = cvt_pk_bf16(r[4], r[5]); w.w = cvt_pk_bf16(r[6], r[7]);
;                 __builtin_nontemporal_store(w, (v4u*)(O + (size_t)(row0 + ai * HALF + m * 16) * FF + col0)); }
	v_add_f32_e32 v163, v163, v176
	v_add_f32_e32 v174, v174, v175
	ds_bpermute_b32 v176, v149, v173
	ds_bpermute_b32 v149, v149, v174
	v_fmamk_f32 v153, v153, 0x3a800000, v172
	v_rsq_f32_e32 v153, v153
	s_waitcnt lgkmcnt(2)
	v_add_f32_e32 v161, v161, v165
	ds_bpermute_b32 v165, v151, v161
	s_waitcnt lgkmcnt(1)
	v_add_f32_e32 v149, v174, v149
	ds_bpermute_b32 v174, v151, v149
	v_mul_f32_e32 v178, v153, v153
	v_pk_mul_f32 v[124:125], v[124:125], v[178:179] op_sel_hi:[1,0]
	s_waitcnt lgkmcnt(1)
	v_add_f32_e32 v161, v161, v165
	v_add_f32_e32 v165, v173, v176
	s_waitcnt lgkmcnt(0)
	v_add_f32_e32 v149, v149, v174
	v_mul_f32_e32 v174, 0xbfb8aa3b, v153
	v_pk_mul_f32 v[180:181], v[128:129], v[174:175] op_sel_hi:[1,0]
	v_pk_mul_f32 v[176:177], v[126:127], v[174:175] op_sel_hi:[1,0]
	v_exp_f32_e32 v180, v180
	v_exp_f32_e32 v181, v181
	v_pk_mul_f32 v[128:129], v[118:119], v[174:175] op_sel_hi:[1,0]
	v_exp_f32_e32 v176, v176
	v_exp_f32_e32 v128, v128
	v_pk_add_f32 v[126:127], v[180:181], 1.0 op_sel_hi:[1,0]
	v_exp_f32_e32 v129, v129
	v_rcp_f32_e32 v126, v126
	v_rcp_f32_e32 v127, v127
	v_exp_f32_e32 v177, v177
	ds_bpermute_b32 v173, v151, v165
	v_fmamk_f32 v155, v155, 0x3a800000, v172
	v_pk_mul_f32 v[124:125], v[124:125], v[126:127]
	v_pk_add_f32 v[126:127], v[128:129], 1.0 op_sel_hi:[1,0]
	v_pk_mul_f32 v[128:129], v[120:121], v[174:175] op_sel_hi:[1,0]
	v_pk_add_f32 v[176:177], v[176:177], 1.0 op_sel_hi:[1,0]
	v_exp_f32_e32 v128, v128
	v_exp_f32_e32 v129, v129
	v_rcp_f32_e32 v126, v126
	v_rcp_f32_e32 v127, v127
	v_rcp_f32_e32 v176, v176
	v_pk_add_f32 v[118:119], v[128:129], 1.0 op_sel_hi:[1,0]
	v_rcp_f32_e32 v177, v177
	v_rcp_f32_e32 v118, v118
	v_rcp_f32_e32 v119, v119
	v_rsq_f32_e32 v155, v155
	v_pk_mul_f32 v[114:115], v[114:115], v[178:179] op_sel_hi:[1,0]
	v_pk_mul_f32 v[122:123], v[122:123], v[178:179] op_sel_hi:[1,0]
	v_pk_mul_f32 v[114:115], v[114:115], v[126:127]
	v_pk_mul_f32 v[116:117], v[116:117], v[178:179] op_sel_hi:[1,0]
	s_waitcnt lgkmcnt(0)
	v_add_f32_e32 v151, v165, v173
	v_ashrrev_i32_e32 v165, 31, v164
	v_pk_mul_f32 v[122:123], v[122:123], v[176:177]
	v_pk_mul_f32 v[116:117], v[116:117], v[118:119]
	v_cvt_pk_bf16_f32 v118, v122, v123
	v_cvt_pk_bf16_f32 v119, v124, v125
	v_cvt_pk_bf16_f32 v120, v114, v115
	v_mov_b64_e32 v[114:115], s[8:9]
	v_cvt_pk_bf16_f32 v121, v116, v117
	v_mad_i64_i32 v[122:123], s[24:25], v162, s44, v[114:115]
	v_lshlrev_b64 v[116:117], 1, v[164:165]
	v_mul_f32_e32 v124, 0xbfb8aa3b, v155
	v_lshl_add_u64 v[122:123], v[122:123], 0, v[116:117]
	global_store_dwordx4 v[122:123], v[118:121], off nt
	v_pk_mul_f32 v[122:123], v[112:113], v[124:125] op_sel_hi:[1,0]
	v_pk_mul_f32 v[126:127], v[110:111], v[124:125] op_sel_hi:[1,0]
	v_exp_f32_e32 v122, v122
	v_exp_f32_e32 v123, v123
	v_pk_mul_f32 v[112:113], v[102:103], v[124:125] op_sel_hi:[1,0]
	v_mul_f32_e32 v118, v155, v155
	v_exp_f32_e32 v112, v112
	v_pk_add_f32 v[110:111], v[122:123], 1.0 op_sel_hi:[1,0]
	v_exp_f32_e32 v113, v113
	v_rcp_f32_e32 v110, v110
	v_rcp_f32_e32 v111, v111
	v_pk_mul_f32 v[108:109], v[108:109], v[118:119] op_sel_hi:[1,0]
	v_exp_f32_e32 v126, v126
	v_exp_f32_e32 v127, v127
	v_pk_mul_f32 v[108:109], v[108:109], v[110:111]
	v_pk_add_f32 v[110:111], v[112:113], 1.0 op_sel_hi:[1,0]
	v_pk_mul_f32 v[112:113], v[104:105], v[124:125] op_sel_hi:[1,0]
	v_rcp_f32_e32 v110, v110
	v_exp_f32_e32 v112, v112
	v_exp_f32_e32 v113, v113
	v_rcp_f32_e32 v111, v111
	v_pk_add_f32 v[120:121], v[126:127], 1.0 op_sel_hi:[1,0]
	v_fmamk_f32 v157, v157, 0x3a800000, v172
	v_pk_add_f32 v[102:103], v[112:113], 1.0 op_sel_hi:[1,0]
	v_rcp_f32_e32 v120, v120
	v_rcp_f32_e32 v102, v102
	v_rcp_f32_e32 v103, v103
	v_rcp_f32_e32 v121, v121
	v_rsq_f32_e32 v157, v157
	v_pk_mul_f32 v[98:99], v[98:99], v[118:119] op_sel_hi:[1,0]
	v_pk_mul_f32 v[106:107], v[106:107], v[118:119] op_sel_hi:[1,0]
	v_pk_mul_f32 v[104:105], v[98:99], v[110:111]
	v_pk_mul_f32 v[98:99], v[100:101], v[118:119] op_sel_hi:[1,0]
	v_pk_mul_f32 v[106:107], v[106:107], v[120:121]
	v_pk_mul_f32 v[102:103], v[98:99], v[102:103]
	v_cvt_pk_bf16_f32 v98, v106, v107
	v_cvt_pk_bf16_f32 v99, v108, v109
	v_cvt_pk_bf16_f32 v100, v104, v105
	v_mul_f32_e32 v104, 0xbfb8aa3b, v157
	v_cvt_pk_bf16_f32 v101, v102, v103
	v_mad_i64_i32 v[102:103], s[24:25], v160, s44, v[114:115]
	v_lshl_add_u64 v[102:103], v[102:103], 0, v[116:117]
	global_store_dwordx4 v[102:103], v[98:101], off nt
	v_pk_mul_f32 v[102:103], v[96:97], v[104:105] op_sel_hi:[1,0]
	v_pk_mul_f32 v[106:107], v[94:95], v[104:105] op_sel_hi:[1,0]
	v_exp_f32_e32 v102, v102
	v_exp_f32_e32 v103, v103
	v_pk_mul_f32 v[96:97], v[86:87], v[104:105] op_sel_hi:[1,0]
	v_mul_f32_e32 v98, v157, v157
	v_exp_f32_e32 v96, v96
	v_pk_add_f32 v[94:95], v[102:103], 1.0 op_sel_hi:[1,0]
	v_exp_f32_e32 v97, v97
	v_rcp_f32_e32 v94, v94
	v_rcp_f32_e32 v95, v95
	v_pk_mul_f32 v[92:93], v[92:93], v[98:99] op_sel_hi:[1,0]
	v_exp_f32_e32 v106, v106
	v_exp_f32_e32 v107, v107
	v_pk_mul_f32 v[92:93], v[92:93], v[94:95]
	v_pk_add_f32 v[94:95], v[96:97], 1.0 op_sel_hi:[1,0]
	v_pk_mul_f32 v[96:97], v[88:89], v[104:105] op_sel_hi:[1,0]
	v_rcp_f32_e32 v94, v94
	v_exp_f32_e32 v96, v96
	v_exp_f32_e32 v97, v97
	v_rcp_f32_e32 v95, v95
	v_pk_add_f32 v[100:101], v[106:107], 1.0 op_sel_hi:[1,0]
	v_fmamk_f32 v159, v159, 0x3a800000, v172
	v_pk_add_f32 v[86:87], v[96:97], 1.0 op_sel_hi:[1,0]
	v_rcp_f32_e32 v100, v100
	v_rcp_f32_e32 v86, v86
	v_rcp_f32_e32 v87, v87
	v_rcp_f32_e32 v101, v101
	v_rsq_f32_e32 v159, v159
	v_pk_mul_f32 v[82:83], v[82:83], v[98:99] op_sel_hi:[1,0]
	v_pk_mul_f32 v[90:91], v[90:91], v[98:99] op_sel_hi:[1,0]
	v_pk_mul_f32 v[88:89], v[82:83], v[94:95]
	v_pk_mul_f32 v[82:83], v[84:85], v[98:99] op_sel_hi:[1,0]
; __device__ __forceinline__ unsigned cvt_pk_bf16(float lo, float hi) { unsigned r; asm volatile("v_cvt_pk_bf16_f32 %0, %1, %2" : "=v"(r) : "v"(lo), "v"(hi)); return r; }
;     __device__ __forceinline__ void operator()(const pg8::f32x4 (&acc)[2][2][4][2], const Unit& u, int wr, int wc, int fr, int fq) const {
;     ...
;             for (int m = 0; m < 4; ++m) { float r[8]; const float rs = rsv[ai * 4 + m]; const float c1 = -1.4426950408889634f * rs, rs2 = rs * rs;
; #pragma unroll
;                 for (int n = 0; n < 2; ++n)
; #pragma unroll
;                     for (int e = 0; e < 4; e += 2) { const f32x2 ag = {acc[ai][0][m][n][e], acc[ai][0][m][n][e + 1]}, au = {acc[ai][1][m][n][e], acc[ai][1][m][n][e + 1]};
;                         const f32x2 t = ag * c1; f32x2 d; d.x = __builtin_amdgcn_exp2f(t.x); d.y = __builtin_amdgcn_exp2f(t.y); d = d + 1.0f;
;                         f32x2 q; q.x = __builtin_amdgcn_rcpf(d.x); q.y = __builtin_amdgcn_rcpf(d.y); const f32x2 o = (ag * au) * rs2 * q; r[4 * n + e] = o.x; r[4 * n + e + 1] = o.y; }
;                 v4u w; w.x = cvt_pk_bf16(r[0], r[1]); w.y = cvt_pk_bf16(r[2], r[3]); w.z = cvt_pk_bf16(r[4], r[5]); w.w = cvt_pk_bf16(r[6], r[7]);
;                 __builtin_nontemporal_store(w, (v4u*)(O + (size_t)(row0 + ai * HALF + m * 16) * FF + col0)); }
	v_pk_mul_f32 v[90:91], v[90:91], v[100:101]
	v_pk_mul_f32 v[86:87], v[82:83], v[86:87]
	v_cvt_pk_bf16_f32 v82, v90, v91
	v_cvt_pk_bf16_f32 v83, v92, v93
	v_cvt_pk_bf16_f32 v84, v88, v89
	v_mul_f32_e32 v88, 0xbfb8aa3b, v159
	v_cvt_pk_bf16_f32 v85, v86, v87
	v_mad_i64_i32 v[86:87], s[24:25], v158, s44, v[114:115]
	v_lshl_add_u64 v[86:87], v[86:87], 0, v[116:117]
	global_store_dwordx4 v[86:87], v[82:85], off nt
	v_pk_mul_f32 v[86:87], v[80:81], v[88:89] op_sel_hi:[1,0]
	v_pk_mul_f32 v[90:91], v[78:79], v[88:89] op_sel_hi:[1,0]
	v_exp_f32_e32 v86, v86
	v_exp_f32_e32 v87, v87
	v_pk_mul_f32 v[80:81], v[70:71], v[88:89] op_sel_hi:[1,0]
	v_mul_f32_e32 v82, v159, v159
	v_exp_f32_e32 v80, v80
	v_pk_add_f32 v[78:79], v[86:87], 1.0 op_sel_hi:[1,0]
	v_exp_f32_e32 v81, v81
	v_rcp_f32_e32 v78, v78
	v_rcp_f32_e32 v79, v79
	v_pk_mul_f32 v[76:77], v[76:77], v[82:83] op_sel_hi:[1,0]
	v_exp_f32_e32 v90, v90
	v_exp_f32_e32 v91, v91
	v_pk_mul_f32 v[76:77], v[76:77], v[78:79]
	v_pk_add_f32 v[78:79], v[80:81], 1.0 op_sel_hi:[1,0]
	v_pk_mul_f32 v[80:81], v[72:73], v[88:89] op_sel_hi:[1,0]
	v_rcp_f32_e32 v78, v78
	v_exp_f32_e32 v80, v80
	v_exp_f32_e32 v81, v81
	v_rcp_f32_e32 v79, v79
	v_pk_add_f32 v[84:85], v[90:91], 1.0 op_sel_hi:[1,0]
	v_fmamk_f32 v163, v163, 0x3a800000, v172
	v_pk_add_f32 v[70:71], v[80:81], 1.0 op_sel_hi:[1,0]
	v_rcp_f32_e32 v84, v84
	v_rcp_f32_e32 v70, v70
	v_rcp_f32_e32 v71, v71
	v_rcp_f32_e32 v85, v85
	v_rsq_f32_e32 v163, v163
	v_pk_mul_f32 v[66:67], v[66:67], v[82:83] op_sel_hi:[1,0]
	v_pk_mul_f32 v[74:75], v[74:75], v[82:83] op_sel_hi:[1,0]
	v_pk_mul_f32 v[72:73], v[66:67], v[78:79]
	v_pk_mul_f32 v[66:67], v[68:69], v[82:83] op_sel_hi:[1,0]
	v_pk_mul_f32 v[74:75], v[74:75], v[84:85]
	v_pk_mul_f32 v[70:71], v[66:67], v[70:71]
	v_cvt_pk_bf16_f32 v66, v74, v75
	v_cvt_pk_bf16_f32 v67, v76, v77
	v_cvt_pk_bf16_f32 v68, v72, v73
	v_mul_f32_e32 v72, 0xbfb8aa3b, v163
	v_cvt_pk_bf16_f32 v69, v70, v71
	v_mad_i64_i32 v[70:71], s[24:25], v156, s44, v[114:115]
	v_lshl_add_u64 v[70:71], v[70:71], 0, v[116:117]
	global_store_dwordx4 v[70:71], v[66:69], off nt
	v_pk_mul_f32 v[70:71], v[64:65], v[72:73] op_sel_hi:[1,0]
	v_pk_mul_f32 v[74:75], v[62:63], v[72:73] op_sel_hi:[1,0]
	v_exp_f32_e32 v70, v70
	v_exp_f32_e32 v71, v71
	v_pk_mul_f32 v[64:65], v[54:55], v[72:73] op_sel_hi:[1,0]
	v_mul_f32_e32 v66, v163, v163
	v_exp_f32_e32 v64, v64
	v_pk_add_f32 v[62:63], v[70:71], 1.0 op_sel_hi:[1,0]
	v_exp_f32_e32 v65, v65
	v_rcp_f32_e32 v62, v62
	v_rcp_f32_e32 v63, v63
	v_pk_mul_f32 v[60:61], v[60:61], v[66:67] op_sel_hi:[1,0]
	v_exp_f32_e32 v74, v74
	v_exp_f32_e32 v75, v75
	v_pk_mul_f32 v[60:61], v[60:61], v[62:63]
	v_pk_add_f32 v[62:63], v[64:65], 1.0 op_sel_hi:[1,0]
	v_pk_mul_f32 v[64:65], v[56:57], v[72:73] op_sel_hi:[1,0]
	v_rcp_f32_e32 v62, v62
	v_exp_f32_e32 v64, v64
	v_exp_f32_e32 v65, v65
	v_rcp_f32_e32 v63, v63
	v_pk_add_f32 v[68:69], v[74:75], 1.0 op_sel_hi:[1,0]
	v_fmamk_f32 v161, v161, 0x3a800000, v172
	v_pk_add_f32 v[54:55], v[64:65], 1.0 op_sel_hi:[1,0]
	v_rcp_f32_e32 v68, v68
	v_rcp_f32_e32 v54, v54
	v_rcp_f32_e32 v55, v55
	v_rcp_f32_e32 v69, v69
	v_rsq_f32_e32 v161, v161
	v_pk_mul_f32 v[50:51], v[50:51], v[66:67] op_sel_hi:[1,0]
	v_pk_mul_f32 v[58:59], v[58:59], v[66:67] op_sel_hi:[1,0]
	v_pk_mul_f32 v[56:57], v[50:51], v[62:63]
	v_pk_mul_f32 v[50:51], v[52:53], v[66:67] op_sel_hi:[1,0]
	v_pk_mul_f32 v[58:59], v[58:59], v[68:69]
	v_pk_mul_f32 v[54:55], v[50:51], v[54:55]
	v_cvt_pk_bf16_f32 v50, v58, v59
	v_cvt_pk_bf16_f32 v51, v60, v61
	v_cvt_pk_bf16_f32 v52, v56, v57
	v_mul_f32_e32 v56, 0xbfb8aa3b, v161
	v_cvt_pk_bf16_f32 v53, v54, v55
	v_mad_i64_i32 v[54:55], s[24:25], v154, s44, v[114:115]
	v_lshl_add_u64 v[54:55], v[54:55], 0, v[116:117]
	global_store_dwordx4 v[54:55], v[50:53], off nt
	v_pk_mul_f32 v[54:55], v[48:49], v[56:57] op_sel_hi:[1,0]
	v_pk_mul_f32 v[58:59], v[46:47], v[56:57] op_sel_hi:[1,0]
	v_exp_f32_e32 v54, v54
	v_exp_f32_e32 v55, v55
	v_pk_mul_f32 v[48:49], v[38:39], v[56:57] op_sel_hi:[1,0]
	v_mul_f32_e32 v50, v161, v161
	v_exp_f32_e32 v48, v48
	v_pk_add_f32 v[46:47], v[54:55], 1.0 op_sel_hi:[1,0]
	v_exp_f32_e32 v49, v49
	v_rcp_f32_e32 v46, v46
	v_rcp_f32_e32 v47, v47
	v_pk_mul_f32 v[44:45], v[44:45], v[50:51] op_sel_hi:[1,0]
	v_exp_f32_e32 v58, v58
	v_exp_f32_e32 v59, v59
	v_pk_mul_f32 v[44:45], v[44:45], v[46:47]
	v_pk_add_f32 v[46:47], v[48:49], 1.0 op_sel_hi:[1,0]
; __device__ __forceinline__ unsigned cvt_pk_bf16(float lo, float hi) { unsigned r; asm volatile("v_cvt_pk_bf16_f32 %0, %1, %2" : "=v"(r) : "v"(lo), "v"(hi)); return r; }
;     __device__ __forceinline__ void operator()(const pg8::f32x4 (&acc)[2][2][4][2], const Unit& u, int wr, int wc, int fr, int fq) const {
;     ...
;             for (int m = 0; m < 4; ++m) { float r[8]; const float rs = rsv[ai * 4 + m]; const float c1 = -1.4426950408889634f * rs, rs2 = rs * rs;
; #pragma unroll
;                 for (int n = 0; n < 2; ++n)
; #pragma unroll
;                     for (int e = 0; e < 4; e += 2) { const f32x2 ag = {acc[ai][0][m][n][e], acc[ai][0][m][n][e + 1]}, au = {acc[ai][1][m][n][e], acc[ai][1][m][n][e + 1]};
;                         const f32x2 t = ag * c1; f32x2 d; d.x = __builtin_amdgcn_exp2f(t.x); d.y = __builtin_amdgcn_exp2f(t.y); d = d + 1.0f;
;                         f32x2 q; q.x = __builtin_amdgcn_rcpf(d.x); q.y = __builtin_amdgcn_rcpf(d.y); const f32x2 o = (ag * au) * rs2 * q; r[4 * n + e] = o.x; r[4 * n + e + 1] = o.y; }
;                 v4u w; w.x = cvt_pk_bf16(r[0], r[1]); w.y = cvt_pk_bf16(r[2], r[3]); w.z = cvt_pk_bf16(r[4], r[5]); w.w = cvt_pk_bf16(r[6], r[7]);
;                 __builtin_nontemporal_store(w, (v4u*)(O + (size_t)(row0 + ai * HALF + m * 16) * FF + col0)); }
	v_pk_mul_f32 v[48:49], v[40:41], v[56:57] op_sel_hi:[1,0]
	v_rcp_f32_e32 v46, v46
	v_exp_f32_e32 v48, v48
	v_exp_f32_e32 v49, v49
	v_rcp_f32_e32 v47, v47
	v_pk_add_f32 v[52:53], v[58:59], 1.0 op_sel_hi:[1,0]
	v_fmamk_f32 v151, v151, 0x3a800000, v172
	v_pk_add_f32 v[38:39], v[48:49], 1.0 op_sel_hi:[1,0]
	v_rcp_f32_e32 v52, v52
	v_rcp_f32_e32 v38, v38
	v_rcp_f32_e32 v39, v39
	v_rcp_f32_e32 v53, v53
	v_rsq_f32_e32 v151, v151
	v_pk_mul_f32 v[34:35], v[34:35], v[50:51] op_sel_hi:[1,0]
	v_pk_mul_f32 v[42:43], v[42:43], v[50:51] op_sel_hi:[1,0]
	v_pk_mul_f32 v[40:41], v[34:35], v[46:47]
	v_pk_mul_f32 v[34:35], v[36:37], v[50:51] op_sel_hi:[1,0]
	v_pk_mul_f32 v[42:43], v[42:43], v[52:53]
	v_pk_mul_f32 v[38:39], v[34:35], v[38:39]
	v_cvt_pk_bf16_f32 v34, v42, v43
	v_cvt_pk_bf16_f32 v35, v44, v45
	v_cvt_pk_bf16_f32 v36, v40, v41
	v_mul_f32_e32 v40, 0xbfb8aa3b, v151
	v_cvt_pk_bf16_f32 v37, v38, v39
	v_mad_i64_i32 v[38:39], s[24:25], v152, s44, v[114:115]
	v_lshl_add_u64 v[38:39], v[38:39], 0, v[116:117]
	global_store_dwordx4 v[38:39], v[34:37], off nt
	v_pk_mul_f32 v[38:39], v[32:33], v[40:41] op_sel_hi:[1,0]
	v_pk_mul_f32 v[42:43], v[30:31], v[40:41] op_sel_hi:[1,0]
	v_exp_f32_e32 v38, v38
	v_exp_f32_e32 v39, v39
	v_pk_mul_f32 v[32:33], v[22:23], v[40:41] op_sel_hi:[1,0]
	v_mul_f32_e32 v34, v151, v151
	v_exp_f32_e32 v32, v32
	v_pk_add_f32 v[30:31], v[38:39], 1.0 op_sel_hi:[1,0]
	v_exp_f32_e32 v33, v33
	v_rcp_f32_e32 v30, v30
	v_rcp_f32_e32 v31, v31
	v_pk_mul_f32 v[28:29], v[28:29], v[34:35] op_sel_hi:[1,0]
	v_exp_f32_e32 v42, v42
	v_exp_f32_e32 v43, v43
	v_pk_mul_f32 v[28:29], v[28:29], v[30:31]
	v_pk_add_f32 v[30:31], v[32:33], 1.0 op_sel_hi:[1,0]
	v_pk_mul_f32 v[32:33], v[24:25], v[40:41] op_sel_hi:[1,0]
	v_rcp_f32_e32 v30, v30
	v_exp_f32_e32 v32, v32
	v_exp_f32_e32 v33, v33
	v_rcp_f32_e32 v31, v31
	v_pk_add_f32 v[36:37], v[42:43], 1.0 op_sel_hi:[1,0]
	v_fmamk_f32 v149, v149, 0x3a800000, v172
	v_pk_add_f32 v[22:23], v[32:33], 1.0 op_sel_hi:[1,0]
	v_rcp_f32_e32 v36, v36
	v_rcp_f32_e32 v22, v22
	v_rcp_f32_e32 v23, v23
	v_rcp_f32_e32 v37, v37
	v_rsq_f32_e32 v149, v149
	v_pk_mul_f32 v[18:19], v[18:19], v[34:35] op_sel_hi:[1,0]
	v_pk_mul_f32 v[26:27], v[26:27], v[34:35] op_sel_hi:[1,0]
	v_pk_mul_f32 v[24:25], v[18:19], v[30:31]
	v_pk_mul_f32 v[18:19], v[20:21], v[34:35] op_sel_hi:[1,0]
	v_pk_mul_f32 v[26:27], v[26:27], v[36:37]
	v_pk_mul_f32 v[22:23], v[18:19], v[22:23]
	v_cvt_pk_bf16_f32 v18, v26, v27
	v_cvt_pk_bf16_f32 v19, v28, v29
	v_cvt_pk_bf16_f32 v20, v24, v25
	v_mul_f32_e32 v24, 0xbfb8aa3b, v149
	v_cvt_pk_bf16_f32 v21, v22, v23
	v_mad_i64_i32 v[22:23], s[24:25], v150, s44, v[114:115]
	v_lshl_add_u64 v[22:23], v[22:23], 0, v[116:117]
	global_store_dwordx4 v[22:23], v[18:21], off nt
	v_pk_mul_f32 v[22:23], v[16:17], v[24:25] op_sel_hi:[1,0]
	v_pk_mul_f32 v[26:27], v[14:15], v[24:25] op_sel_hi:[1,0]
	v_exp_f32_e32 v22, v22
	v_exp_f32_e32 v23, v23
	v_pk_mul_f32 v[16:17], v[6:7], v[24:25] op_sel_hi:[1,0]
	v_mul_f32_e32 v18, v149, v149
	v_exp_f32_e32 v16, v16
	v_pk_add_f32 v[14:15], v[22:23], 1.0 op_sel_hi:[1,0]
	v_exp_f32_e32 v17, v17
	v_rcp_f32_e32 v14, v14
	v_rcp_f32_e32 v15, v15
	v_pk_mul_f32 v[12:13], v[12:13], v[18:19] op_sel_hi:[1,0]
	v_exp_f32_e32 v26, v26
	v_exp_f32_e32 v27, v27
	v_pk_mul_f32 v[12:13], v[12:13], v[14:15]
	v_pk_add_f32 v[14:15], v[16:17], 1.0 op_sel_hi:[1,0]
	v_pk_mul_f32 v[16:17], v[8:9], v[24:25] op_sel_hi:[1,0]
	v_rcp_f32_e32 v14, v14
	v_exp_f32_e32 v16, v16
	v_exp_f32_e32 v17, v17
	v_rcp_f32_e32 v15, v15
	v_pk_add_f32 v[20:21], v[26:27], 1.0 op_sel_hi:[1,0]
	v_pk_mul_f32 v[2:3], v[2:3], v[18:19] op_sel_hi:[1,0]
	v_pk_add_f32 v[6:7], v[16:17], 1.0 op_sel_hi:[1,0]
	v_rcp_f32_e32 v20, v20
	v_rcp_f32_e32 v6, v6
	v_rcp_f32_e32 v7, v7
	v_rcp_f32_e32 v21, v21
	v_pk_mul_f32 v[8:9], v[2:3], v[14:15]
	v_pk_mul_f32 v[2:3], v[4:5], v[18:19] op_sel_hi:[1,0]
	v_pk_mul_f32 v[10:11], v[10:11], v[18:19] op_sel_hi:[1,0]
	v_pk_mul_f32 v[6:7], v[2:3], v[6:7]
	v_pk_mul_f32 v[10:11], v[10:11], v[20:21]
	s_nop 0
	v_cvt_pk_bf16_f32 v2, v10, v11
	v_cvt_pk_bf16_f32 v3, v12, v13
	v_cvt_pk_bf16_f32 v4, v8, v9
	v_cvt_pk_bf16_f32 v5, v6, v7
	v_mad_i64_i32 v[6:7], s[24:25], v148, s44, v[114:115]
	v_lshl_add_u64 v[6:7], v[6:7], 0, v[116:117]
	global_store_dwordx4 v[6:7], v[2:5], off nt
	s_cbranch_vccnz .LBB0_687
	s_andn2_b64 vcc, exec, s[4:5]
	s_cbranch_vccnz .LBB0_686
	s_barrier
	s_branch .LBB0_686

; #define PG8_STAGE(bufoff, gbase, voff) do { _Pragma("unroll") for (int _i = 0; _i < 2; ++_i) \
;         __builtin_amdgcn_global_load_lds((const unsigned*)((const char*)(gbase) + (voff)[_i]), (PG8_LAS unsigned*)(lds + (bufoff) + ldsw + _i * 8192), 16, 0, 0); } while (0)
; #define PG8_WAIT_V(n) asm volatile("s_waitcnt vmcnt(" #n ")" ::: "memory")
; #define PG8_BAR __builtin_amdgcn_s_barrier()
; template <class Epi, class Sched, bool ALIGN_EPI = false, bool SP2 = false>
; __device__ __forceinline__ void gemm_phase(PG8_LAS unsigned char* lds, const Gemm g, const Sched& S, const Epi& E) {
;     ...
;     for (int i = 0; i < 2; ++i) { int R, C; stage_rc(tid * 16 + i * 8192, R, C); const int Rb = Epi::PERM ? ((R & ~31) + perm32(R & 31)) : R;
;         voffA[i] = (unsigned)(R * g.lda + C) * 2u; voffB[i] = (unsigned)(Rb * g.ldb + C) * 2u; }
;     const size_t kstep = (size_t)(BK * 2);
;     const size_t hstepA = (size_t)HALF * g.lda * 2, hstepB = (size_t)HALF * g.ldb * 2;
;     const size_t tstepA = 2 * hstepA, tstepB = 2 * hstepB;
;     const unsigned ldsw = (unsigned)wid * 1024u;
;     const int aoff = lds_byte(wr * 64 + fr, fq * 8), boff = lds_byte(wc * 32 + fr, fq * 8);
;     ...
;     const char* cA = (const char*)g.A + (size_t)cur.g * g.gsA * 2 + (size_t)cur.pm * tstepA; const char* cB = (const char*)g.Bt + (size_t)cur.g * g.gsB * 2 + (size_t)cur.pn * tstepB;
;     S.a_ready(cur);
;     if constexpr (SP2) {
;         PG8_STAGE(PG8_SB(0, 0), cB, voffB); PG8_STAGE(PG8_SB(0, 1), cB + hstepB, voffB); PG8_STAGE(PG8_SA(0, 0), cA, voffA); PG8_STAGE(PG8_SA(0, 1), cA + hstepA, voffA);
;         if (wr == 1) PG8_BAR;
;         PG8_WAIT_V(2); PG8_BAR;
;         PG8_STAGE(PG8_SB(1, 0), cB + kstep, voffB); PG8_STAGE(PG8_SA(1, 0), cA + kstep, voffA); PG8_STAGE(PG8_SB(1, 1), cB + hstepB + kstep, voffB);
;         PG8_WAIT_V(6); PG8_BAR;
.LBB0_759:
	v_cndmask_b32_e64 v1, 0, 1, s[4:5]
	v_cmp_ne_u32_e64 s[6:7], 1, v1
	s_andn2_b64 vcc, exec, s[4:5]
	s_cbranch_vccnz .LBB0_799
	v_ashrrev_i32_e32 v2, 31, v10
	v_lshrrev_b32_e32 v2, 26, v2
	v_add_u32_e32 v2, v10, v2
	v_ashrrev_i32_e32 v11, 6, v2
	v_bfe_i32 v2, v10, 27, 1
	v_lshlrev_b32_e32 v1, 4, v10
	v_lshrrev_b32_e32 v2, 22, v2
	v_add_u32_e32 v2, v1, v2
	v_and_b32_e32 v2, 0xfffffc00, v2
	v_sub_u32_e32 v2, v1, v2
	v_lshrrev_b32_e32 v3, 4, v2
	v_bitop3_b32 v2, v3, v2, 32 bitop3:0x6c
	v_ashrrev_i32_e32 v4, 31, v2
	v_lshrrev_b32_e32 v4, 26, v4
	v_lshlrev_b32_e32 v3, 3, v11
	v_add_u32_e32 v4, v2, v4
	v_and_b32_e32 v3, -16, v3
	v_ashrrev_i32_e32 v13, 6, v4
	v_and_b32_e32 v4, 0xc0, v4
	v_add_u32_e32 v3, v13, v3
	v_lshlrev_b32_e32 v5, 5, v11
	v_sub_u32_e32 v2, v2, v4
	v_mov_b32_e32 v4, 1
	v_and_b32_e32 v12, 32, v5
	v_ashrrev_i16_sdwa v2, v4, sext(v2) dst_sel:DWORD dst_unused:UNUSED_PAD src0_sel:DWORD src1_sel:BYTE_0
	v_lshlrev_b32_e32 v5, 1, v3
	v_lshrrev_b32_e32 v6, 2, v3
	v_and_b32_e32 v7, 3, v13
	s_mov_b32 s0, 0xffffe0
	v_bfe_i32 v14, v2, 0, 16
	v_and_b32_e32 v5, 24, v5
	v_and_b32_e32 v6, 4, v6
	v_and_or_b32 v7, v3, s0, v7
	s_movk_i32 s4, 0xb00
	v_add_u32_e32 v2, v12, v14
	v_or3_b32 v5, v7, v6, v5
	v_mul_lo_u32 v3, v3, s4
	v_add_lshl_u32 v138, v2, v3, 1
	v_mul_u32_u24_e32 v3, 0xb00, v5
	v_add_u32_e32 v1, 0x2000, v1
	v_add_lshl_u32 v140, v3, v2, 1
	v_ashrrev_i32_e32 v2, 31, v1
	v_lshrrev_b32_e32 v2, 22, v2
	v_add_u32_e32 v2, v1, v2
	v_ashrrev_i32_e32 v15, 10, v2
	v_mul_i32_i24_e32 v2, 0x400, v15
	v_sub_u32_e32 v1, v1, v2
	v_lshrrev_b32_e32 v2, 4, v1
	v_bitop3_b32 v1, v2, v1, 32 bitop3:0x6c
	v_ashrrev_i32_e32 v3, 31, v1
	s_add_u32 s2, s78, 0x13c00000
	v_lshrrev_b32_e32 v3, 26, v3
	s_addc_u32 s3, s79, 0
	v_lshlrev_b32_e32 v2, 3, v15
	v_add_u32_e32 v3, v1, v3
	s_add_u32 s33, s78, 0x4600000
	v_and_b32_e32 v2, -16, v2
	v_ashrrev_i32_e32 v16, 6, v3
	v_lshlrev_b32_e32 v5, 5, v15
	s_addc_u32 s36, s79, 0
	s_ashr_i32 s9, s8, 6
	v_add_u32_e32 v2, v16, v2
	v_and_b32_e32 v17, 32, v5
	v_and_b32_e32 v3, 0xc0, v3
	v_and_b32_e32 v5, 3, v16
	v_sub_u32_e32 v1, v1, v3
	v_and_or_b32 v5, v2, s0, v5
	s_ashr_i32 s10, s8, 8
	s_lshl_b32 s0, s9, 10
	s_mul_i32 s12, s51, 0x160000
	v_ashrrev_i16_sdwa v1, v4, sext(v1) dst_sel:DWORD dst_unused:UNUSED_PAD src0_sel:DWORD src1_sel:BYTE_0
	v_lshlrev_b32_e32 v3, 1, v2
	v_lshrrev_b32_e32 v4, 2, v2
	s_mul_hi_i32 s1, s51, 0x160000
	s_add_u32 s28, s33, s12
	v_bfe_i32 v18, v1, 0, 16
	v_and_b32_e32 v3, 24, v3
	v_and_b32_e32 v4, 4, v4
	s_addc_u32 s29, s36, s1
	s_add_i32 s1, s0, 0
	v_add_u32_e32 v1, v17, v18
	v_or3_b32 v3, v5, v4, v3
	v_mul_lo_u32 v2, v2, s4
	s_add_i32 m0, s1, 0x10000
	v_add_lshl_u32 v142, v1, v2, 1
	v_mul_u32_u24_e32 v2, 0xb00, v3
	v_and_b32_e32 v216, 63, v10
	v_lshrrev_b32_e32 v217, 5, v216
	v_lshlrev_b32_e32 v217, 1, v217
	v_and_b32_e32 v138, 3, v216
	v_xor_b32_e32 v138, v138, v217
	v_lshrrev_b32_e32 v217, 2, v216
	v_lshl_add_u32 v138, v138, 4, v217
	v_lshlrev_b32_e32 v138, 4, v138
	s_lshr_b32 s100, s9, 1
	s_mul_i32 s100, s100, 0x58
	s_and_b32 s101, s9, 1
	s_add_i32 s100, s100, s101
	s_lshl_b32 s100, s100, 10
	v_add_u32_e32 v138, s100, v138
	v_add_u32_e32 v142, 0x58000, v138
	s_mov_b64 s[100:101], 0x800
	global_load_lds_dwordx4 v140, s[28:29]
	s_add_i32 m0, s1, 0x12000
	v_add_lshl_u32 v144, v2, v1, 1
	s_add_u32 s12, s28, 0xb0000
	global_load_lds_dwordx4 v144, s[28:29]
	s_addc_u32 s13, s29, 0
	s_add_i32 m0, s1, 0x14000
	s_mul_i32 s11, s52, 0x160000
	global_load_lds_dwordx4 v140, s[12:13]
	s_add_i32 m0, s1, 0x16000
	s_mul_hi_i32 s5, s52, 0x160000
	s_add_u32 s26, s2, s11
	s_addc_u32 s27, s3, s5
	s_add_i32 s37, s1, 0x2000
	global_load_lds_dwordx4 v144, s[12:13]
	s_mov_b32 m0, s1
	s_add_u32 s12, s26, 0xb0000
	global_load_lds_dwordx4 v138, s[26:27]
	s_mov_b32 m0, s37
	s_addc_u32 s13, s27, 0
	s_add_i32 s38, s1, 0x4000
	global_load_lds_dwordx4 v142, s[26:27]
	s_mov_b32 m0, s38
	s_add_i32 s39, s1, 0x6000
	global_load_lds_dwordx4 v138, s[12:13]
	s_mov_b32 m0, s39
	v_mov_b32_e32 v141, 0
	global_load_lds_dwordx4 v142, s[12:13]
	v_mov_b32_e32 v145, v141
	v_mov_b32_e32 v139, v141
	v_mov_b32_e32 v143, v141
	s_cmp_eq_u32 s10, 1
	s_mov_b32 s5, 0
	v_lshl_add_u64 v[8:9], s[28:29], 0, v[140:141]
	v_lshl_add_u64 v[6:7], s[28:29], 0, v[144:145]
	v_lshl_add_u64 v[2:3], s[26:27], 0, v[138:139]
	s_cselect_b64 s[14:15], -1, 0
	s_cmp_lg_u32 s10, 1
	v_lshl_add_u64 v[4:5], s[26:27], 0, v[142:143]
	s_cbranch_scc1 .LBB0_762
	s_barrier
.LBB0_762:
	s_add_u32 s16, s78, 0x7c00000
	s_addc_u32 s17, s79, 0
	s_add_u32 s18, s78, 0x5800000
	s_mov_b64 s[20:21], 0x80
	s_addc_u32 s19, s79, 0
	s_and_b32 s40, s9, 3
	s_add_i32 m0, s1, 0x18000
	v_lshl_add_u64 v[8:9], v[8:9], 0, s[20:21]
	s_lshl_b32 s9, s10, 13
	s_lshl_b32 s11, s40, 12
	s_waitcnt vmcnt(2)
	s_barrier
	global_load_lds_dwordx4 v[8:9], off
	v_lshl_add_u64 v[6:7], v[6:7], 0, s[20:21]
	s_add_i32 m0, s1, 0x1a000
	s_add_i32 s41, s1, 0x8000
	s_add_i32 s42, s1, 0xa000
	global_load_lds_dwordx4 v[6:7], off
	v_lshl_add_u64 v[2:3], v[2:3], 0, s[100:101]
	s_mov_b32 m0, s41
	s_add_u32 s12, s28, 0xb0080
	global_load_lds_dwordx4 v[2:3], off
	v_lshl_add_u64 v[2:3], v[4:5], 0, s[100:101]
	s_mov_b32 m0, s42
	s_addc_u32 s13, s29, 0
	global_load_lds_dwordx4 v[2:3], off
	s_add_i32 m0, s1, 0x1c000
	v_lshl_add_u64 v[2:3], s[12:13], 0, v[140:141]
	global_load_lds_dwordx4 v[2:3], off
	v_lshl_add_u64 v[2:3], s[12:13], 0, v[144:145]
	s_add_i32 m0, s1, 0x1e000
	s_cmpk_lt_u32 s8, 0x100
	global_load_lds_dwordx4 v[2:3], off
	v_bfe_u32 v2, v10, 4, 2
	v_and_b32_e32 v3, 15, v10
	v_lshlrev_b32_e32 v5, 4, v2
	v_lshl_or_b32 v1, s10, 6, v3
	v_lshl_or_b32 v3, v3, 6, v5
	v_lshlrev_b32_e32 v5, 2, v10
	v_and_b32_e32 v5, 32, v5
	v_lshlrev_b32_e32 v4, 3, v2
	v_bitop3_b32 v6, v3, s9, v5 bitop3:0xde
	v_bitop3_b32 v162, v3, s11, v5 bitop3:0xde
	v_cmp_eq_u32_e64 s[8:9], 0, v2
	v_lshrrev_b32_e32 v3, 1, v11
	v_mul_lo_u32 v2, v13, s4
	s_mov_b32 s24, 0xb000
	v_mad_u64_u32 v[2:3], s[12:13], v3, s24, v[2:3]
	v_or_b32_e32 v2, v2, v12
	s_mov_b64 s[10:11], 0xb0080
	v_add_lshl_u32 v2, v2, v14, 1
	v_mov_b32_e32 v3, v141
	v_lshl_add_u64 v[146:147], v[2:3], 0, s[10:11]
	v_lshrrev_b32_e32 v3, 1, v15
	v_mul_lo_u32 v2, v16, s4
	v_mad_u64_u32 v[2:3], s[12:13], v3, s24, v[2:3]
	v_or_b32_e32 v2, v2, v17
	s_waitcnt vmcnt(6)
	v_add_lshl_u32 v2, v2, v18, 1
	v_mov_b32_e32 v3, v141
	s_cselect_b64 s[22:23], -1, 0
	v_lshl_add_u64 v[148:149], v[2:3], 0, s[10:11]
	v_add_u32_e32 v146, 0xb0800, v138
	v_mov_b32_e32 v147, 0
	v_add_u32_e32 v148, 0xb0800, v142
	v_mov_b32_e32 v149, 0
	s_add_i32 s46, 0, 0x10000
	s_add_i32 s47, 0, 0x14000
	v_mbcnt_lo_u32_b32 v2, -1, 0
	v_lshl_or_b32 v163, s40, 5, v4
	s_ashr_i32 s43, s82, 31
	s_mov_b32 s44, s82
	s_ashr_i32 s45, s96, 31
	v_mov_b64_e32 v[150:151], 0x200
	v_mov_b64_e32 v[152:153], 0x1ff
	v_add_u32_e32 v164, s46, v162
	v_add_u32_e32 v165, s47, v162
	v_add_u32_e32 v166, 0, v6
	v_mbcnt_hi_u32_b32 v167, -1, v2
	s_mov_b32 s48, 0
	s_barrier
	s_branch .LBB0_765

; #define PG8_STAGE(bufoff, gbase, voff) do { _Pragma("unroll") for (int _i = 0; _i < 2; ++_i) \
;         __builtin_amdgcn_global_load_lds((const unsigned*)((const char*)(gbase) + (voff)[_i]), (PG8_LAS unsigned*)(lds + (bufoff) + ldsw + _i * 8192), 16, 0, 0); } while (0)
; #define PG8_LDA(dst, b, h) do { _Pragma("unroll") for (int m = 0; m < 4; ++m) _Pragma("unroll") for (int k = 0; k < 2; ++k) dst[m][k] = *(const PG8_LAS bf16x8*)(lds + PG8_SA(b, h) + aoff + m * 2048 + k * 1024); } while (0)
; #define PG8_LDB(dst, b, h) do { _Pragma("unroll") for (int n = 0; n < 2; ++n) _Pragma("unroll") for (int k = 0; k < 2; ++k) dst[n][k] = *(const PG8_LAS bf16x8*)(lds + PG8_SB(b, h) + boff + n * 2048 + k * 1024); } while (0)
; #define PG8_MMA(ai, bj, At, Bt) do { __builtin_amdgcn_s_setprio(1); _Pragma("unroll") for (int m = 0; m < 4; ++m) _Pragma("unroll") for (int n = 0; n < 2; ++n) _Pragma("unroll") for (int k = 0; k < 2; ++k) \
;         acc[ai][bj][m][n] = __builtin_amdgcn_mfma_f32_16x16x32_bf16(Bt[n][k], At[m][k], acc[ai][bj][m][n], 0, 0, 0); __builtin_amdgcn_s_setprio(0); } while (0)
; #define PG8_WAIT_V(n) asm volatile("s_waitcnt vmcnt(" #n ")" ::: "memory")
; #define PG8_WAIT_L(n) asm volatile("s_waitcnt lgkmcnt(" #n ")" ::: "memory")
; #define PG8_BAR __builtin_amdgcn_s_barrier()
; #define PG8_SCHED __builtin_amdgcn_sched_barrier(0)
; template <class Epi, class Sched, bool ALIGN_EPI = false, bool SP2 = false>
; __device__ __forceinline__ void gemm_phase(PG8_LAS unsigned char* lds, const Gemm g, const Sched& S, const Epi& E) {
;     ...
;             PG8_LDB(B0, 0, 0); PG8_LDB(B1, 0, 1); PG8_SCHED; PG8_LDA(At, 0, 0); PG8_STAGE(PG8_SA(1, 1), a1 + hstepA, voffA);
;             PG8_WAIT_V(8); PG8_WAIT_L(0); PG8_BAR; PG8_MMA(0, 0, At, B0); PG8_MMA(0, 1, At, B1); PG8_BAR; PG8_SCHED;
;             PG8_LDA(At, 0, 1); PG8_STAGE(PG8_SB(0, 0), b2, voffB); PG8_STAGE(PG8_SB(0, 1), b2 + hstepB, voffB); PG8_STAGE(PG8_SA(0, 0), a2, voffA);
.LBB0_776:
	ds_read_b128 v[130:133], v164
	ds_read_b128 v[134:137], v164 offset:1024
	ds_read_b128 v[154:157], v164 offset:2048
	ds_read_b128 v[158:161], v164 offset:3072
	ds_read_b128 v[168:171], v165
	ds_read_b128 v[172:175], v165 offset:1024
	ds_read_b128 v[176:179], v165 offset:2048
	ds_read_b128 v[180:183], v165 offset:3072
	s_add_u32 s28, s26, 0x1000
	s_addc_u32 s29, s27, 0
	s_cmp_eq_u32 s54, 40
	s_cselect_b32 s35, s13, s29
	s_cselect_b32 s34, s12, s28
	s_cselect_b32 s31, s25, s53
	s_cselect_b32 s30, s24, s4
	v_lshl_add_u64 v[216:217], s[26:27], 0, v[146:147]
	s_add_i32 m0, s1, 0xc000
	ds_read_b128 v[184:187], v166
	ds_read_b128 v[188:191], v166 offset:1024
	ds_read_b128 v[192:195], v166 offset:2048
	ds_read_b128 v[196:199], v166 offset:3072
	ds_read_b128 v[200:203], v166 offset:4096
	ds_read_b128 v[204:207], v166 offset:5120
	ds_read_b128 v[208:211], v166 offset:6144
	ds_read_b128 v[212:215], v166 offset:7168
	global_load_lds_dwordx4 v[216:217], off
	v_lshl_add_u64 v[216:217], s[26:27], 0, v[148:149]
	s_add_i32 m0, s1, 0xe000
	s_nop 0
	global_load_lds_dwordx4 v[216:217], off
	s_waitcnt vmcnt(8)
	s_waitcnt lgkmcnt(0)
	s_barrier
	s_setprio 1
	s_waitcnt lgkmcnt(0)
	v_mfma_f32_16x16x32_bf16 v[126:129], v[130:133], v[184:187], v[126:129]
	v_mfma_f32_16x16x32_bf16 v[122:125], v[154:157], v[184:187], v[122:125]
	v_mfma_f32_16x16x32_bf16 v[110:113], v[130:133], v[192:195], v[110:113]
	v_mfma_f32_16x16x32_bf16 v[106:109], v[154:157], v[192:195], v[106:109]
	v_mfma_f32_16x16x32_bf16 v[94:97], v[130:133], v[200:203], v[94:97]
	v_mfma_f32_16x16x32_bf16 v[90:93], v[154:157], v[200:203], v[90:93]
	v_mfma_f32_16x16x32_bf16 v[78:81], v[130:133], v[208:211], v[78:81]
	v_mfma_f32_16x16x32_bf16 v[74:77], v[154:157], v[208:211], v[74:77]
	v_mfma_f32_16x16x32_bf16 v[126:129], v[134:137], v[188:191], v[126:129]
	v_mfma_f32_16x16x32_bf16 v[122:125], v[158:161], v[188:191], v[122:125]
	v_mfma_f32_16x16x32_bf16 v[110:113], v[134:137], v[196:199], v[110:113]
	v_mfma_f32_16x16x32_bf16 v[106:109], v[158:161], v[196:199], v[106:109]
	v_mfma_f32_16x16x32_bf16 v[94:97], v[134:137], v[204:207], v[94:97]
	v_mfma_f32_16x16x32_bf16 v[90:93], v[158:161], v[204:207], v[90:93]
	v_mfma_f32_16x16x32_bf16 v[78:81], v[134:137], v[212:215], v[78:81]
	v_mfma_f32_16x16x32_bf16 v[74:77], v[158:161], v[212:215], v[74:77]
	s_setprio 0
	s_setprio 1
	v_mfma_f32_16x16x32_bf16 v[118:121], v[168:171], v[184:187], v[118:121]
	v_mfma_f32_16x16x32_bf16 v[114:117], v[176:179], v[184:187], v[114:117]
	v_mfma_f32_16x16x32_bf16 v[102:105], v[168:171], v[192:195], v[102:105]
	v_mfma_f32_16x16x32_bf16 v[98:101], v[176:179], v[192:195], v[98:101]
	v_mfma_f32_16x16x32_bf16 v[86:89], v[168:171], v[200:203], v[86:89]
	v_mfma_f32_16x16x32_bf16 v[82:85], v[176:179], v[200:203], v[82:85]
	v_mfma_f32_16x16x32_bf16 v[70:73], v[168:171], v[208:211], v[70:73]
	v_mfma_f32_16x16x32_bf16 v[66:69], v[176:179], v[208:211], v[66:69]
	v_mfma_f32_16x16x32_bf16 v[118:121], v[172:175], v[188:191], v[118:121]
	v_mfma_f32_16x16x32_bf16 v[114:117], v[180:183], v[188:191], v[114:117]
	v_mfma_f32_16x16x32_bf16 v[102:105], v[172:175], v[196:199], v[102:105]
	v_mfma_f32_16x16x32_bf16 v[98:101], v[180:183], v[196:199], v[98:101]
	v_mfma_f32_16x16x32_bf16 v[86:89], v[172:175], v[204:207], v[86:89]
	v_mfma_f32_16x16x32_bf16 v[82:85], v[180:183], v[204:207], v[82:85]
	v_mfma_f32_16x16x32_bf16 v[70:73], v[172:175], v[212:215], v[70:73]
	v_mfma_f32_16x16x32_bf16 v[66:69], v[180:183], v[212:215], v[66:69]
	s_setprio 0
	s_barrier
	s_add_i32 s26, s46, s0
	v_lshl_add_u64 v[216:217], s[30:31], 0, v[140:141]
	s_mov_b32 m0, s26
	ds_read_b128 v[184:187], v166 offset:16384
	ds_read_b128 v[188:191], v166 offset:17408
	ds_read_b128 v[192:195], v166 offset:18432
	ds_read_b128 v[196:199], v166 offset:19456
	ds_read_b128 v[200:203], v166 offset:20480
	ds_read_b128 v[204:207], v166 offset:21504
	ds_read_b128 v[208:211], v166 offset:22528
	ds_read_b128 v[212:215], v166 offset:23552
	global_load_lds_dwordx4 v[216:217], off
	s_add_i32 m0, s26, 0x2000
	s_add_u32 s26, s30, 0xb0000
	v_lshl_add_u64 v[218:219], s[30:31], 0, v[144:145]
	s_addc_u32 s27, s31, 0
	s_add_i32 s55, s47, s0
	global_load_lds_dwordx4 v[218:219], off
	v_lshl_add_u64 v[220:221], s[26:27], 0, v[140:141]
	s_mov_b32 m0, s55
	v_lshl_add_u64 v[222:223], s[34:35], 0, v[142:143]
	global_load_lds_dwordx4 v[220:221], off
	v_lshl_add_u64 v[220:221], s[26:27], 0, v[144:145]
	s_add_i32 m0, s55, 0x2000
	s_nop 0
	global_load_lds_dwordx4 v[220:221], off
	v_lshl_add_u64 v[220:221], s[34:35], 0, v[138:139]
	s_mov_b32 m0, s1
	s_nop 0
	global_load_lds_dwordx4 v[220:221], off
	s_mov_b32 m0, s37
	s_nop 0
	global_load_lds_dwordx4 v[222:223], off
	s_waitcnt vmcnt(8)
	s_waitcnt lgkmcnt(0)
	s_barrier
; #define PG8_STAGE(bufoff, gbase, voff) do { _Pragma("unroll") for (int _i = 0; _i < 2; ++_i) \
;         __builtin_amdgcn_global_load_lds((const unsigned*)((const char*)(gbase) + (voff)[_i]), (PG8_LAS unsigned*)(lds + (bufoff) + ldsw + _i * 8192), 16, 0, 0); } while (0)
; #define PG8_LDA(dst, b, h) do { _Pragma("unroll") for (int m = 0; m < 4; ++m) _Pragma("unroll") for (int k = 0; k < 2; ++k) dst[m][k] = *(const PG8_LAS bf16x8*)(lds + PG8_SA(b, h) + aoff + m * 2048 + k * 1024); } while (0)
; #define PG8_LDB(dst, b, h) do { _Pragma("unroll") for (int n = 0; n < 2; ++n) _Pragma("unroll") for (int k = 0; k < 2; ++k) dst[n][k] = *(const PG8_LAS bf16x8*)(lds + PG8_SB(b, h) + boff + n * 2048 + k * 1024); } while (0)
; #define PG8_MMA(ai, bj, At, Bt) do { __builtin_amdgcn_s_setprio(1); _Pragma("unroll") for (int m = 0; m < 4; ++m) _Pragma("unroll") for (int n = 0; n < 2; ++n) _Pragma("unroll") for (int k = 0; k < 2; ++k) \
;         acc[ai][bj][m][n] = __builtin_amdgcn_mfma_f32_16x16x32_bf16(Bt[n][k], At[m][k], acc[ai][bj][m][n], 0, 0, 0); __builtin_amdgcn_s_setprio(0); } while (0)
; #define PG8_WAIT_V(n) asm volatile("s_waitcnt vmcnt(" #n ")" ::: "memory")
; #define PG8_WAIT_L(n) asm volatile("s_waitcnt lgkmcnt(" #n ")" ::: "memory")
; #define PG8_BAR __builtin_amdgcn_s_barrier()
; #define PG8_SCHED __builtin_amdgcn_sched_barrier(0)
; template <class Epi, class Sched, bool ALIGN_EPI = false, bool SP2 = false>
; __device__ __forceinline__ void gemm_phase(PG8_LAS unsigned char* lds, const Gemm g, const Sched& S, const Epi& E) {
;     ...
;             PG8_LDA(At, 0, 1); PG8_STAGE(PG8_SB(0, 0), b2, voffB); PG8_STAGE(PG8_SB(0, 1), b2 + hstepB, voffB); PG8_STAGE(PG8_SA(0, 0), a2, voffA);
;             PG8_WAIT_V(8); PG8_WAIT_L(0); PG8_BAR; PG8_MMA(1, 0, At, B0); PG8_MMA(1, 1, At, B1); PG8_BAR; PG8_SCHED;
;             PG8_LDB(B0, 1, 0); PG8_LDB(B1, 1, 1); PG8_SCHED; PG8_LDA(At, 1, 0); PG8_STAGE(PG8_SA(0, 1), a2 + hstepA, voffA);
;             PG8_WAIT_V(8); PG8_WAIT_L(0); PG8_BAR; PG8_MMA(0, 0, At, B0); PG8_MMA(0, 1, At, B1); PG8_BAR; PG8_SCHED;
	s_setprio 1
	s_waitcnt lgkmcnt(0)
	v_mfma_f32_16x16x32_bf16 v[62:65], v[130:133], v[184:187], v[62:65]
	v_mfma_f32_16x16x32_bf16 v[58:61], v[154:157], v[184:187], v[58:61]
	v_mfma_f32_16x16x32_bf16 v[46:49], v[130:133], v[192:195], v[46:49]
	v_mfma_f32_16x16x32_bf16 v[42:45], v[154:157], v[192:195], v[42:45]
	v_mfma_f32_16x16x32_bf16 v[30:33], v[130:133], v[200:203], v[30:33]
	v_mfma_f32_16x16x32_bf16 v[26:29], v[154:157], v[200:203], v[26:29]
	v_mfma_f32_16x16x32_bf16 v[14:17], v[130:133], v[208:211], v[14:17]
	v_mfma_f32_16x16x32_bf16 v[10:13], v[154:157], v[208:211], v[10:13]
	v_mfma_f32_16x16x32_bf16 v[62:65], v[134:137], v[188:191], v[62:65]
	v_mfma_f32_16x16x32_bf16 v[58:61], v[158:161], v[188:191], v[58:61]
	v_mfma_f32_16x16x32_bf16 v[46:49], v[134:137], v[196:199], v[46:49]
	v_mfma_f32_16x16x32_bf16 v[42:45], v[158:161], v[196:199], v[42:45]
	v_mfma_f32_16x16x32_bf16 v[30:33], v[134:137], v[204:207], v[30:33]
	v_mfma_f32_16x16x32_bf16 v[26:29], v[158:161], v[204:207], v[26:29]
	v_mfma_f32_16x16x32_bf16 v[14:17], v[134:137], v[212:215], v[14:17]
	v_mfma_f32_16x16x32_bf16 v[10:13], v[158:161], v[212:215], v[10:13]
	s_setprio 0
	s_setprio 1
	v_mfma_f32_16x16x32_bf16 v[54:57], v[168:171], v[184:187], v[54:57]
	v_mfma_f32_16x16x32_bf16 v[50:53], v[176:179], v[184:187], v[50:53]
	v_mfma_f32_16x16x32_bf16 v[38:41], v[168:171], v[192:195], v[38:41]
	v_mfma_f32_16x16x32_bf16 v[34:37], v[176:179], v[192:195], v[34:37]
	v_mfma_f32_16x16x32_bf16 v[22:25], v[168:171], v[200:203], v[22:25]
	v_mfma_f32_16x16x32_bf16 v[18:21], v[176:179], v[200:203], v[18:21]
	v_mfma_f32_16x16x32_bf16 v[6:9], v[168:171], v[208:211], v[6:9]
	v_mfma_f32_16x16x32_bf16 v[2:5], v[176:179], v[208:211], v[2:5]
	v_mfma_f32_16x16x32_bf16 v[54:57], v[172:175], v[188:191], v[54:57]
	v_mfma_f32_16x16x32_bf16 v[50:53], v[180:183], v[188:191], v[50:53]
	v_mfma_f32_16x16x32_bf16 v[38:41], v[172:175], v[196:199], v[38:41]
	v_mfma_f32_16x16x32_bf16 v[34:37], v[180:183], v[196:199], v[34:37]
	v_mfma_f32_16x16x32_bf16 v[22:25], v[172:175], v[204:207], v[22:25]
	v_mfma_f32_16x16x32_bf16 v[18:21], v[180:183], v[204:207], v[18:21]
	v_mfma_f32_16x16x32_bf16 v[6:9], v[172:175], v[212:215], v[6:9]
	v_mfma_f32_16x16x32_bf16 v[2:5], v[180:183], v[212:215], v[2:5]
	s_setprio 0
	s_barrier
	s_add_i32 s55, 0, 0x18000
	s_add_i32 s56, 0, 0x1c000
	v_add_u32_e32 v158, s55, v162
	v_add_u32_e32 v180, s56, v162
	ds_read_b128 v[130:133], v158
	ds_read_b128 v[134:137], v158 offset:1024
	ds_read_b128 v[154:157], v158 offset:2048
	ds_read_b128 v[158:161], v158 offset:3072
	ds_read_b128 v[168:171], v180
	ds_read_b128 v[172:175], v180 offset:1024
	ds_read_b128 v[176:179], v180 offset:2048
	ds_read_b128 v[180:183], v180 offset:3072
	s_add_u32 s26, s34, 0xb0000
	s_addc_u32 s27, s35, 0
	s_mov_b32 m0, s38
	v_lshl_add_u64 v[224:225], s[26:27], 0, v[138:139]
	ds_read_b128 v[184:187], v166 offset:32768
	ds_read_b128 v[188:191], v166 offset:33792
	ds_read_b128 v[192:195], v166 offset:34816
	ds_read_b128 v[196:199], v166 offset:35840
	ds_read_b128 v[200:203], v166 offset:36864
	ds_read_b128 v[204:207], v166 offset:37888
	ds_read_b128 v[208:211], v166 offset:38912
	ds_read_b128 v[212:215], v166 offset:39936
	global_load_lds_dwordx4 v[224:225], off
	v_lshl_add_u64 v[224:225], s[26:27], 0, v[142:143]
	s_mov_b32 m0, s39
	s_nop 0
	global_load_lds_dwordx4 v[224:225], off
	s_waitcnt vmcnt(8)
	s_waitcnt lgkmcnt(0)
	s_barrier
	s_setprio 1
	s_waitcnt lgkmcnt(0)
	v_mfma_f32_16x16x32_bf16 v[126:129], v[130:133], v[184:187], v[126:129]
	v_mfma_f32_16x16x32_bf16 v[122:125], v[154:157], v[184:187], v[122:125]
	v_mfma_f32_16x16x32_bf16 v[110:113], v[130:133], v[192:195], v[110:113]
	v_mfma_f32_16x16x32_bf16 v[106:109], v[154:157], v[192:195], v[106:109]
	v_mfma_f32_16x16x32_bf16 v[94:97], v[130:133], v[200:203], v[94:97]
	v_mfma_f32_16x16x32_bf16 v[90:93], v[154:157], v[200:203], v[90:93]
	v_mfma_f32_16x16x32_bf16 v[78:81], v[130:133], v[208:211], v[78:81]
	v_mfma_f32_16x16x32_bf16 v[74:77], v[154:157], v[208:211], v[74:77]
	v_mfma_f32_16x16x32_bf16 v[126:129], v[134:137], v[188:191], v[126:129]
	v_mfma_f32_16x16x32_bf16 v[122:125], v[158:161], v[188:191], v[122:125]
	v_mfma_f32_16x16x32_bf16 v[110:113], v[134:137], v[196:199], v[110:113]
	v_mfma_f32_16x16x32_bf16 v[106:109], v[158:161], v[196:199], v[106:109]
	v_mfma_f32_16x16x32_bf16 v[94:97], v[134:137], v[204:207], v[94:97]
	v_mfma_f32_16x16x32_bf16 v[90:93], v[158:161], v[204:207], v[90:93]
	v_mfma_f32_16x16x32_bf16 v[78:81], v[134:137], v[212:215], v[78:81]
	v_mfma_f32_16x16x32_bf16 v[74:77], v[158:161], v[212:215], v[74:77]
	s_setprio 0
	s_setprio 1
	v_mfma_f32_16x16x32_bf16 v[118:121], v[168:171], v[184:187], v[118:121]
	v_mfma_f32_16x16x32_bf16 v[114:117], v[176:179], v[184:187], v[114:117]
	v_mfma_f32_16x16x32_bf16 v[102:105], v[168:171], v[192:195], v[102:105]
	v_mfma_f32_16x16x32_bf16 v[98:101], v[176:179], v[192:195], v[98:101]
	v_mfma_f32_16x16x32_bf16 v[86:89], v[168:171], v[200:203], v[86:89]
	v_mfma_f32_16x16x32_bf16 v[82:85], v[176:179], v[200:203], v[82:85]
	v_mfma_f32_16x16x32_bf16 v[70:73], v[168:171], v[208:211], v[70:73]
	v_mfma_f32_16x16x32_bf16 v[66:69], v[176:179], v[208:211], v[66:69]
	v_mfma_f32_16x16x32_bf16 v[118:121], v[172:175], v[188:191], v[118:121]
	v_mfma_f32_16x16x32_bf16 v[114:117], v[180:183], v[188:191], v[114:117]
	v_mfma_f32_16x16x32_bf16 v[102:105], v[172:175], v[196:199], v[102:105]
	v_mfma_f32_16x16x32_bf16 v[98:101], v[180:183], v[196:199], v[98:101]
	v_mfma_f32_16x16x32_bf16 v[86:89], v[172:175], v[204:207], v[86:89]
	v_mfma_f32_16x16x32_bf16 v[82:85], v[180:183], v[204:207], v[82:85]
	v_mfma_f32_16x16x32_bf16 v[70:73], v[172:175], v[212:215], v[70:73]
	v_mfma_f32_16x16x32_bf16 v[66:69], v[180:183], v[212:215], v[66:69]
	s_setprio 0
	s_barrier
; #define PG8_STAGE(bufoff, gbase, voff) do { _Pragma("unroll") for (int _i = 0; _i < 2; ++_i) \
;         __builtin_amdgcn_global_load_lds((const unsigned*)((const char*)(gbase) + (voff)[_i]), (PG8_LAS unsigned*)(lds + (bufoff) + ldsw + _i * 8192), 16, 0, 0); } while (0)
; #define PG8_LDA(dst, b, h) do { _Pragma("unroll") for (int m = 0; m < 4; ++m) _Pragma("unroll") for (int k = 0; k < 2; ++k) dst[m][k] = *(const PG8_LAS bf16x8*)(lds + PG8_SA(b, h) + aoff + m * 2048 + k * 1024); } while (0)
; #define PG8_MMA(ai, bj, At, Bt) do { __builtin_amdgcn_s_setprio(1); _Pragma("unroll") for (int m = 0; m < 4; ++m) _Pragma("unroll") for (int n = 0; n < 2; ++n) _Pragma("unroll") for (int k = 0; k < 2; ++k) \
;         acc[ai][bj][m][n] = __builtin_amdgcn_mfma_f32_16x16x32_bf16(Bt[n][k], At[m][k], acc[ai][bj][m][n], 0, 0, 0); __builtin_amdgcn_s_setprio(0); } while (0)
; #define PG8_WAIT_V(n) asm volatile("s_waitcnt vmcnt(" #n ")" ::: "memory")
; #define PG8_WAIT_L(n) asm volatile("s_waitcnt lgkmcnt(" #n ")" ::: "memory")
; #define PG8_BAR __builtin_amdgcn_s_barrier()
; #define PG8_SCHED __builtin_amdgcn_sched_barrier(0)
; template <class Epi, class Sched, bool ALIGN_EPI = false, bool SP2 = false>
; __device__ __forceinline__ void gemm_phase(PG8_LAS unsigned char* lds, const Gemm g, const Sched& S, const Epi& E) {
;     ...
;         for (int t = 0; t < nt; t += 2) {
;             const bool last = (t == nt - 2);
;             const char* a1 = cA + (size_t)(t + 1) * kstep;
;             const char* a2 = last ? nA : cA + (size_t)(t + 2) * kstep; const char* b2 = last ? nB : cB + (size_t)(t + 2) * kstep;
;     ...
;             PG8_WAIT_V(8); PG8_WAIT_L(0); PG8_BAR; PG8_MMA(0, 0, At, B0); PG8_MMA(0, 1, At, B1); PG8_BAR; PG8_SCHED;
;             PG8_LDA(At, 1, 1); PG8_STAGE(PG8_SB(1, 0), b3, voffB); PG8_STAGE(PG8_SB(1, 1), b3 + hstepB, voffB); PG8_STAGE(PG8_SA(1, 0), a3, voffA);
;             PG8_WAIT_V(8); PG8_WAIT_L(0); PG8_BAR; PG8_MMA(1, 0, At, B0); PG8_MMA(1, 1, At, B1); PG8_BAR; PG8_SCHED;
	s_add_i32 s26, s55, s0
	v_lshl_add_u64 v[216:217], v[216:217], 0, s[20:21]
	s_mov_b32 m0, s26
	ds_read_b128 v[184:187], v166 offset:49152
	ds_read_b128 v[188:191], v166 offset:50176
	ds_read_b128 v[192:195], v166 offset:51200
	ds_read_b128 v[196:199], v166 offset:52224
	ds_read_b128 v[200:203], v166 offset:53248
	ds_read_b128 v[204:207], v166 offset:54272
	ds_read_b128 v[208:211], v166 offset:55296
	ds_read_b128 v[212:215], v166 offset:56320
	global_load_lds_dwordx4 v[216:217], off
	s_add_i32 m0, s26, 0x2000
	s_add_u32 s26, s30, 0xb0080
	v_lshl_add_u64 v[216:217], v[218:219], 0, s[20:21]
	s_addc_u32 s27, s31, 0
	s_add_i32 s30, s56, s0
	global_load_lds_dwordx4 v[216:217], off
	v_lshl_add_u64 v[216:217], s[26:27], 0, v[140:141]
	s_mov_b32 m0, s30
	s_nop 0
	global_load_lds_dwordx4 v[216:217], off
	v_lshl_add_u64 v[216:217], s[26:27], 0, v[144:145]
	s_add_i32 m0, s30, 0x2000
	s_nop 0
	global_load_lds_dwordx4 v[216:217], off
	v_lshl_add_u64 v[216:217], v[220:221], 0, s[100:101]
	s_mov_b32 m0, s41
	s_nop 0
	global_load_lds_dwordx4 v[216:217], off
	v_lshl_add_u64 v[216:217], v[222:223], 0, s[100:101]
	s_mov_b32 m0, s42
	s_nop 0
	global_load_lds_dwordx4 v[216:217], off
	s_waitcnt vmcnt(8)
	s_waitcnt lgkmcnt(0)
	s_barrier
	s_setprio 1
	s_waitcnt lgkmcnt(0)
	v_mfma_f32_16x16x32_bf16 v[62:65], v[130:133], v[184:187], v[62:65]
	v_mfma_f32_16x16x32_bf16 v[58:61], v[154:157], v[184:187], v[58:61]
	v_mfma_f32_16x16x32_bf16 v[46:49], v[130:133], v[192:195], v[46:49]
	v_mfma_f32_16x16x32_bf16 v[42:45], v[154:157], v[192:195], v[42:45]
	v_mfma_f32_16x16x32_bf16 v[30:33], v[130:133], v[200:203], v[30:33]
	v_mfma_f32_16x16x32_bf16 v[26:29], v[154:157], v[200:203], v[26:29]
	v_mfma_f32_16x16x32_bf16 v[14:17], v[130:133], v[208:211], v[14:17]
	v_mfma_f32_16x16x32_bf16 v[10:13], v[154:157], v[208:211], v[10:13]
	v_mfma_f32_16x16x32_bf16 v[62:65], v[134:137], v[188:191], v[62:65]
	v_mfma_f32_16x16x32_bf16 v[58:61], v[158:161], v[188:191], v[58:61]
	v_mfma_f32_16x16x32_bf16 v[46:49], v[134:137], v[196:199], v[46:49]
	v_mfma_f32_16x16x32_bf16 v[42:45], v[158:161], v[196:199], v[42:45]
	v_mfma_f32_16x16x32_bf16 v[30:33], v[134:137], v[204:207], v[30:33]
	v_mfma_f32_16x16x32_bf16 v[26:29], v[158:161], v[204:207], v[26:29]
	v_mfma_f32_16x16x32_bf16 v[14:17], v[134:137], v[212:215], v[14:17]
	v_mfma_f32_16x16x32_bf16 v[10:13], v[158:161], v[212:215], v[10:13]
	s_setprio 0
	s_setprio 1
	v_mfma_f32_16x16x32_bf16 v[54:57], v[168:171], v[184:187], v[54:57]
	v_mfma_f32_16x16x32_bf16 v[50:53], v[176:179], v[184:187], v[50:53]
	v_mfma_f32_16x16x32_bf16 v[38:41], v[168:171], v[192:195], v[38:41]
	v_mfma_f32_16x16x32_bf16 v[34:37], v[176:179], v[192:195], v[34:37]
	v_mfma_f32_16x16x32_bf16 v[22:25], v[168:171], v[200:203], v[22:25]
	v_mfma_f32_16x16x32_bf16 v[18:21], v[176:179], v[200:203], v[18:21]
	v_mfma_f32_16x16x32_bf16 v[6:9], v[168:171], v[208:211], v[6:9]
	v_mfma_f32_16x16x32_bf16 v[2:5], v[176:179], v[208:211], v[2:5]
	v_mfma_f32_16x16x32_bf16 v[54:57], v[172:175], v[188:191], v[54:57]
	v_mfma_f32_16x16x32_bf16 v[50:53], v[180:183], v[188:191], v[50:53]
	v_mfma_f32_16x16x32_bf16 v[38:41], v[172:175], v[196:199], v[38:41]
	v_mfma_f32_16x16x32_bf16 v[34:37], v[180:183], v[196:199], v[34:37]
	v_mfma_f32_16x16x32_bf16 v[22:25], v[172:175], v[204:207], v[22:25]
	v_mfma_f32_16x16x32_bf16 v[18:21], v[180:183], v[204:207], v[18:21]
	v_mfma_f32_16x16x32_bf16 v[6:9], v[172:175], v[212:215], v[6:9]
	v_mfma_f32_16x16x32_bf16 v[2:5], v[180:183], v[212:215], v[2:5]
	s_setprio 0
	s_barrier
	s_add_i32 s54, s54, 2
	s_add_u32 s4, s4, 0x100
	s_addc_u32 s53, s53, 0
	s_cmp_gt_u32 s54, 41
	s_mov_b64 s[26:27], s[28:29]
	s_cbranch_scc0 .LBB0_776
	s_and_b64 vcc, exec, s[22:23]
	s_cbranch_vccz .LBB0_779
	s_barrier

; __global__ void __launch_bounds__(NTHR, 2) hybrid_fwd(Args args) {
	.amdhsa_kernel _Z10hybrid_fwd4Args
		.amdhsa_group_segment_fixed_size 0
		.amdhsa_private_segment_fixed_size 0
		.amdhsa_kernarg_size 512
		.amdhsa_user_sgpr_count 2
		.amdhsa_user_sgpr_dispatch_ptr 0
		.amdhsa_user_sgpr_queue_ptr 0
		.amdhsa_user_sgpr_kernarg_segment_ptr 1
		.amdhsa_user_sgpr_dispatch_id 0
		.amdhsa_user_sgpr_kernarg_preload_length 0
		.amdhsa_user_sgpr_kernarg_preload_offset 0
		.amdhsa_user_sgpr_private_segment_size 0
		.amdhsa_uses_dynamic_stack 0
		.amdhsa_enable_private_segment 0
		.amdhsa_system_sgpr_workgroup_id_x 1
		.amdhsa_system_sgpr_workgroup_id_y 0
		.amdhsa_system_sgpr_workgroup_id_z 0
		.amdhsa_system_sgpr_workgroup_info 0
		.amdhsa_system_vgpr_workitem_id 0
		.amdhsa_next_free_vgpr 255
		.amdhsa_next_free_sgpr 102
		.amdhsa_accum_offset 256
		.amdhsa_reserve_vcc 1
		.amdhsa_float_round_mode_32 0
		.amdhsa_float_round_mode_16_64 0
		.amdhsa_float_denorm_mode_32 3
		.amdhsa_float_denorm_mode_16_64 3
		.amdhsa_dx10_clamp 1
		.amdhsa_ieee_mode 1
		.amdhsa_fp16_overflow 0
		.amdhsa_tg_split 0
		.amdhsa_exception_fp_ieee_invalid_op 0
		.amdhsa_exception_fp_denorm_src 0
		.amdhsa_exception_fp_ieee_div_zero 0
		.amdhsa_exception_fp_ieee_overflow 0
		.amdhsa_exception_fp_ieee_underflow 0
		.amdhsa_exception_fp_ieee_inexact 0
		.amdhsa_exception_int_div_zero 0
	.end_amdhsa_kernel

; __global__ void __launch_bounds__(NTHR, 2) hybrid_fwd(Args args) {
amdhsa.kernels:
  - .agpr_count:     0
    .args:
      - .offset:         0
        .size:           256
        .value_kind:     by_value
      - .offset:         256
        .size:           4
        .value_kind:     hidden_block_count_x
      - .offset:         260
        .size:           4
        .value_kind:     hidden_block_count_y
      - .offset:         264
        .size:           4
        .value_kind:     hidden_block_count_z
      - .offset:         268
        .size:           2
        .value_kind:     hidden_group_size_x
      - .offset:         270
        .size:           2
        .value_kind:     hidden_group_size_y
      - .offset:         272
        .size:           2
        .value_kind:     hidden_group_size_z
      - .offset:         274
        .size:           2
        .value_kind:     hidden_remainder_x
      - .offset:         276
        .size:           2
        .value_kind:     hidden_remainder_y
      - .offset:         278
        .size:           2
        .value_kind:     hidden_remainder_z
      - .offset:         296
        .size:           8
        .value_kind:     hidden_global_offset_x
      - .offset:         304
        .size:           8
        .value_kind:     hidden_global_offset_y
      - .offset:         312
        .size:           8
        .value_kind:     hidden_global_offset_z
      - .offset:         320
        .size:           2
        .value_kind:     hidden_grid_dims
      - .offset:         376
        .size:           4
        .value_kind:     hidden_dynamic_lds_size
    .group_segment_fixed_size: 0
    .kernarg_segment_align: 8
    .kernarg_segment_size: 512
    .language:       OpenCL C
    .language_version:
      - 2
      - 0
    .max_flat_workgroup_size: 512
    .name:           _Z10hybrid_fwd4Args
    .private_segment_fixed_size: 0
    .sgpr_count:     108
    .sgpr_spill_count: 29
    .symbol:         _Z10hybrid_fwd4Args.kd
    .uniform_work_group_size: 1
    .uses_dynamic_stack: false
    .vgpr_count:     255
    .vgpr_spill_count: 0
    .wavefront_size: 64
